# diff-attn ALiBi bias: abs folded into v_fma source modifier (drops 16 v_and + 2 v_mov per key tile)
# speedup vs baseline: 1.0388x; 1.0047x over previous
; #define MFMA(a, b, c) __builtin_amdgcn_mfma_f32_32x32x16_bf16((a), (b), (c), 0, 0, 0)
; template <int KS, int NMAP, int EB, int NKB, int MODE>
; DI void attn_unit(unsigned char* smem, const AttnArgs& a, int t0, int head, int ehalf) {
;     ...
;     for (int kb = 0; kb < NKB; ++kb) {
;       bf16x8 pf[NMAP][2];
;       f32x16 cinit;
;       if (MODE == AT_DIFF) {
;         const float dbase = (float)(posq - kt * KT - 32 * kb - 8 * h);
; #pragma unroll
;         for (int i = 0; i < 16; ++i) { const float d = dbase - (float)(16 * (i >> 3) + (i & 7)); cinit[i] = fmaf(-slope2, fabsf(d), negM); }
;       } else {
; #pragma unroll
;         for (int i = 0; i < 16; ++i) cinit[i] = negM;
;       }
; #pragma unroll
;       for (int c = 0; c < NMAP; ++c) {
;         f32x16 sacc;
; #pragma unroll
;         for (int s = 0; s < KS; ++s) {
;           const bf16x8 kf = *(const bf16x8*)(ks + (32 * kb + r) * KP + (c * KS + s) * 32 + 16 * h);
;           const bf16x8 qv = QLDS ? *(const bf16x8*)(qs + qoff + (c * KS + s) * 32) : qf[QLDS ? 0 : c * KS + s];
;           sacc = (s == 0) ? MFMA(kf, qv, cinit) : MFMA(kf, qv, sacc);
;         }
;         float ls = 0.f;
; #pragma unroll
;         for (int i = 0; i < 16; ++i) { sacc[i] = __builtin_amdgcn_exp2f(sacc[i]); ls += sacc[i]; }
;         lsum[c] += ls;
; #pragma unroll
;         for (int cc = 0; cc < 2; ++cc) { u32x4 u;
; #pragma unroll
;           for (int j = 0; j < 4; ++j) u[j] = pk2(sacc[8 * cc + 2 * j], sacc[8 * cc + 2 * j + 1]);
;           pf[c][cc] = __builtin_bit_cast(bf16x8, u); }
;       }
; #pragma unroll
;       for (int eb = 0; eb < EB; ++eb)
; #pragma unroll
;         for (int cc = 0; cc < 2; ++cc) {
;           const bf16x8 vf = *(const bf16x8*)(vs + (eb * 32 + r) * VP + (32 * kb + 16 * cc + 8 * h) * 2);
; #pragma unroll
;           for (int c = 0; c < NMAP; ++c) oacc[c][eb] = MFMA(vf, pf[c][cc], oacc[c][eb]);
;         }
;     }
.LBB0_408:
	s_mulk_i32 s0, 0x4a00
	v_cvt_f32_i32_e32 v128, v198
	v_add_u32_e32 v187, s0, v197
	v_add_u32_e32 v199, v187, v195
	ds_read_b128 v[200:203], v175 offset:37888
	ds_read_b128 v[204:207], v175 offset:37920
	ds_read_b128 v[208:211], v199
	ds_read_b128 v[212:215], v199 offset:32
	v_add_f32_e32 v129, -1.0, v128
	v_pk_add_f32 v[130:131], v[128:129], s[38:39] op_sel_hi:[0,1]
	v_pk_add_f32 v[132:133], v[128:129], s[78:79] op_sel_hi:[0,1]
	v_pk_add_f32 v[134:135], v[128:129], s[80:81] op_sel_hi:[0,1]
	v_pk_add_f32 v[136:137], v[128:129], s[82:83] op_sel_hi:[0,1]
	v_pk_add_f32 v[138:139], v[128:129], s[84:85] op_sel_hi:[0,1]
	v_pk_add_f32 v[140:141], v[128:129], s[86:87] op_sel_hi:[0,1]
	v_pk_add_f32 v[142:143], v[128:129], s[88:89] op_sel_hi:[0,1]
	v_fma_f32 v143, v180, |v143|, v168
	v_fma_f32 v142, v180, |v142|, v168
	v_fma_f32 v141, v180, |v141|, v168
	v_fma_f32 v140, v180, |v140|, v168
	v_fma_f32 v139, v180, |v139|, v168
	v_fma_f32 v138, v180, |v138|, v168
	v_fma_f32 v137, v180, |v137|, v168
	v_fma_f32 v136, v180, |v136|, v168
	v_fma_f32 v135, v180, |v135|, v168
	v_fma_f32 v134, v180, |v134|, v168
	v_fma_f32 v133, v180, |v133|, v168
	v_fma_f32 v132, v180, |v132|, v168
	v_fma_f32 v131, v180, |v131|, v168
	v_fma_f32 v130, v180, |v130|, v168
	v_fma_f32 v129, v180, |v129|, v168
	v_fma_f32 v128, v180, |v128|, v168
	s_mov_b64 s[0:1], 0x2000
	s_add_i32 s12, s12, 1
	s_waitcnt lgkmcnt(1)
	v_mfma_f32_32x32x16_bf16 v[144:159], v[208:211], v[200:203], v[128:143]
	v_lshl_add_u64 v[184:185], v[184:185], 0, s[0:1]
	s_add_i32 s0, s50, s12
	v_subrev_u32_e32 v198, 32, v198
	v_add_u32_e32 v186, 32, v186
	s_cmp_ge_i32 s0, s13
	s_waitcnt lgkmcnt(0)
	v_mfma_f32_32x32x16_bf16 v[144:159], v[212:215], v[204:207], v[144:159]
	ds_read_b128 v[200:203], v175 offset:37952
	ds_read_b128 v[204:207], v199 offset:64
	s_waitcnt lgkmcnt(0)
	v_mfma_f32_32x32x16_bf16 v[144:159], v[204:207], v[200:203], v[144:159]
	ds_read_b128 v[200:203], v175 offset:37984
	ds_read_b128 v[204:207], v199 offset:96
	s_waitcnt lgkmcnt(0)
	v_mfma_f32_32x32x16_bf16 v[144:159], v[204:207], v[200:203], v[144:159]
	s_nop 11
	v_exp_f32_e32 v201, v144
	v_exp_f32_e32 v203, v145
	v_exp_f32_e32 v205, v146
	v_exp_f32_e32 v207, v147
	v_exp_f32_e32 v209, v148
	v_exp_f32_e32 v211, v149
	v_exp_f32_e32 v213, v150
	v_exp_f32_e32 v215, v151
	ds_read_b128 v[144:147], v175 offset:38016
	ds_read_b128 v[148:151], v199 offset:128
	s_waitcnt lgkmcnt(0)
	v_mfma_f32_32x32x16_bf16 v[128:143], v[148:151], v[144:147], v[128:143]
	ds_read_b128 v[144:147], v175 offset:38048
	ds_read_b128 v[148:151], v199 offset:160
	v_exp_f32_e32 v221, v152
	v_exp_f32_e32 v153, v153
	v_exp_f32_e32 v223, v154
	v_exp_f32_e32 v155, v155
	v_exp_f32_e32 v225, v156
	v_exp_f32_e32 v157, v157
	s_waitcnt lgkmcnt(0)
	v_mfma_f32_32x32x16_bf16 v[128:143], v[148:151], v[144:147], v[128:143]
	ds_read_b128 v[144:147], v175 offset:38080
	ds_read_b128 v[148:151], v199 offset:192
	v_exp_f32_e32 v227, v158
	v_exp_f32_e32 v159, v159
	s_waitcnt lgkmcnt(0)
	v_mfma_f32_32x32x16_bf16 v[128:143], v[148:151], v[144:147], v[128:143]
	ds_read_b128 v[144:147], v175 offset:38112
	ds_read_b128 v[148:151], v199 offset:224
	s_waitcnt lgkmcnt(0)
	v_mfma_f32_32x32x16_bf16 v[128:143], v[148:151], v[144:147], v[128:143]
	v_cvt_pk_bf16_f32 v144, v201, v203
	v_cvt_pk_bf16_f32 v145, v205, v207
	v_cvt_pk_bf16_f32 v146, v209, v211
	v_cvt_pk_bf16_f32 v147, v213, v215
	s_nop 7
	v_exp_f32_e32 v200, v128
	v_exp_f32_e32 v202, v129
	v_exp_f32_e32 v204, v130
	v_exp_f32_e32 v206, v131
	v_exp_f32_e32 v208, v132
	v_pk_add_f32 v[128:129], v[200:201], 0 op_sel_hi:[1,0]
	v_exp_f32_e32 v210, v133
	v_pk_add_f32 v[128:129], v[202:203], v[128:129]
	v_exp_f32_e32 v212, v134
	v_pk_add_f32 v[128:129], v[204:205], v[128:129]
	v_exp_f32_e32 v214, v135
	v_pk_add_f32 v[128:129], v[206:207], v[128:129]
	v_exp_f32_e32 v220, v136
	v_pk_add_f32 v[128:129], v[208:209], v[128:129]
	v_exp_f32_e32 v152, v137
	v_pk_add_f32 v[128:129], v[210:211], v[128:129]
	v_exp_f32_e32 v222, v138
	v_pk_add_f32 v[128:129], v[212:213], v[128:129]
	v_exp_f32_e32 v154, v139
	v_pk_add_f32 v[128:129], v[214:215], v[128:129]
	v_exp_f32_e32 v224, v140
	v_pk_add_f32 v[128:129], v[220:221], v[128:129]
	v_exp_f32_e32 v156, v141
	v_pk_add_f32 v[128:129], v[152:153], v[128:129]
	v_exp_f32_e32 v226, v142
	v_pk_add_f32 v[128:129], v[222:223], v[128:129]
	v_exp_f32_e32 v158, v143
	v_pk_add_f32 v[128:129], v[154:155], v[128:129]
	v_cvt_pk_bf16_f32 v136, v200, v202
	v_pk_add_f32 v[128:129], v[224:225], v[128:129]
	v_cvt_pk_bf16_f32 v137, v204, v206
	v_pk_add_f32 v[128:129], v[156:157], v[128:129]
	v_cvt_pk_bf16_f32 v138, v208, v210
	v_pk_add_f32 v[128:129], v[226:227], v[128:129]
	v_cvt_pk_bf16_f32 v139, v212, v214
	v_pk_add_f32 v[132:133], v[158:159], v[128:129]
	v_cvt_pk_bf16_f32 v128, v221, v153
	v_pk_add_f32 v[176:177], v[176:177], v[132:133]
	v_cvt_pk_bf16_f32 v132, v220, v152
	v_add_u32_e32 v152, v187, v196
	ds_read_b128 v[140:143], v152 offset:8704
	ds_read_b128 v[148:151], v152 offset:8736
	s_waitcnt lgkmcnt(1)
	v_mfma_f32_32x32x16_bf16 v[96:111], v[140:143], v[144:147], v[96:111]
	v_cvt_pk_bf16_f32 v129, v223, v155
	v_cvt_pk_bf16_f32 v130, v225, v157
	v_cvt_pk_bf16_f32 v131, v227, v159
	v_cvt_pk_bf16_f32 v133, v222, v154
	v_cvt_pk_bf16_f32 v134, v224, v156
	v_cvt_pk_bf16_f32 v135, v226, v158
	v_mfma_f32_32x32x16_bf16 v[112:127], v[140:143], v[136:139], v[112:127]
	ds_read_b128 v[140:143], v152 offset:11264
	s_waitcnt lgkmcnt(0)
	v_mfma_f32_32x32x16_bf16 v[64:79], v[140:143], v[144:147], v[64:79]
	v_mfma_f32_32x32x16_bf16 v[80:95], v[140:143], v[136:139], v[80:95]
	ds_read_b128 v[140:143], v152 offset:11296
	s_waitcnt lgkmcnt(0)
	v_mfma_f32_32x32x16_bf16 v[64:79], v[140:143], v[128:131], v[64:79]
	v_mfma_f32_32x32x16_bf16 v[80:95], v[140:143], v[132:135], v[80:95]
	ds_read_b128 v[140:143], v152 offset:13824
	s_waitcnt lgkmcnt(0)
	v_mfma_f32_32x32x16_bf16 v[32:47], v[140:143], v[144:147], v[32:47]
	v_mfma_f32_32x32x16_bf16 v[48:63], v[140:143], v[136:139], v[48:63]
	ds_read_b128 v[140:143], v152 offset:13856
	s_waitcnt lgkmcnt(0)
	v_mfma_f32_32x32x16_bf16 v[32:47], v[140:143], v[128:131], v[32:47]
	v_mfma_f32_32x32x16_bf16 v[48:63], v[140:143], v[132:135], v[48:63]
	ds_read_b128 v[140:143], v152 offset:16384
	s_waitcnt lgkmcnt(0)
	v_mfma_f32_32x32x16_bf16 v[16:31], v[140:143], v[136:139], v[16:31]
	ds_read_b128 v[136:139], v152 offset:16416
	s_waitcnt lgkmcnt(0)
	s_barrier
	v_mfma_f32_32x32x16_bf16 v[0:15], v[140:143], v[144:147], v[0:15]
	v_mfma_f32_32x32x16_bf16 v[96:111], v[148:151], v[128:131], v[96:111]
	v_mfma_f32_32x32x16_bf16 v[112:127], v[148:151], v[132:135], v[112:127]
	v_mfma_f32_32x32x16_bf16 v[0:15], v[136:139], v[128:131], v[0:15]
	v_mfma_f32_32x32x16_bf16 v[16:31], v[136:139], v[132:135], v[16:31]
	s_cbranch_scc1 .LBB0_396
